# combine and late rec-norm loops: straight-line copy with next trip's loads issued before current trip's wait (two register sets), on v18
# baseline (speedup 1.0000x reference)
.LBB0_580:
	s_cmp_lt_i32 s78, 7
	s_cselect_b64 s[2:3], -1, 0
	s_and_b64 s[2:3], s[2:3], s[0:1]
	s_andn2_b64 vcc, exec, s[2:3]
	s_cbranch_vccnz .LBB0_588
	v_readlane_b32 s0, v246, 48
	v_lshl_add_u32 v6, s74, 9, v171
	s_lshl_b32 s8, s0, 9
	s_mov_b32 s0, 0x100000
	v_readlane_b32 s1, v246, 49
	v_cmp_gt_i32_e32 vcc, s0, v6
	s_and_saveexec_b64 s[0:1], vcc
	s_cbranch_execz .LBB0_584
	v_lshrrev_b32_e32 v8, 3, v170
	v_mov_b32_e32 v1, 0
	v_lshlrev_b32_e32 v0, 4, v170
	v_lshl_add_u64 v[2:3], s[94:95], 0, v[0:1]
	v_lshl_add_u64 v[4:5], s[30:31], 0, v[0:1]
	s_mov_b64 s[4:5], 0
	v_lshlrev_b32_e32 v0, 2, v8
	s_movk_i32 s6, 0xc00
	s_mov_b32 s7, 0xfffff
	v_mov_b32_e32 v7, v6
	s_and_b64 vcc, exec, s[92:93]
	s_cbranch_vccz .LBB0_583
	v_ashrrev_i32_e32 v20, 6, v7
	v_ashrrev_i32_e32 v21, 31, v20
	v_lshlrev_b64 v[12:13], 5, v[20:21]
	v_lshl_add_u64 v[12:13], s[34:35], 0, v[12:13]
	v_lshl_add_u64 v[12:13], v[12:13], 0, v[0:1]
	v_add_co_u32_e32 v14, vcc, 0x80000, v12
	v_mad_i64_i32 v[16:17], s[10:11], v20, s6, v[2:3]
	s_nop 0
	v_addc_co_u32_e32 v15, vcc, 0, v13, vcc
	global_load_dwordx4 v[8:11], v[16:17], off offset:1024 nt
	global_load_dword v34, v[12:13], off
	v_add_co_u32_e32 v12, vcc, 0x100000, v12
	v_add_u32_e32 v7, s8, v7
	s_nop 0
	v_addc_co_u32_e32 v13, vcc, 0, v13, vcc
	global_load_dword v35, v[14:15], off
	global_load_dword v36, v[12:13], off
	s_nop 0
	global_load_dwordx4 v[12:15], v[16:17], off nt
	s_nop 0
	global_load_dwordx4 v[16:19], v[16:17], off offset:2048 nt
	v_lshlrev_b64 v[20:21], 10, v[20:21]
	v_lshl_add_u64 v[20:21], v[4:5], 0, v[20:21]
	v_ashrrev_i32_e32 v100, 6, v7
	v_ashrrev_i32_e32 v101, 31, v100
	v_lshlrev_b64 v[92:93], 5, v[100:101]
	v_lshl_add_u64 v[92:93], s[34:35], 0, v[92:93]
	v_lshl_add_u64 v[92:93], v[92:93], 0, v[0:1]
	v_add_co_u32_e32 v94, vcc, 0x80000, v92
	v_mad_i64_i32 v[96:97], s[10:11], v100, s6, v[2:3]
	s_nop 0
	v_addc_co_u32_e32 v95, vcc, 0, v93, vcc
	global_load_dwordx4 v[88:91], v[96:97], off offset:1024 nt
	global_load_dword v114, v[92:93], off
	v_add_co_u32_e32 v92, vcc, 0x100000, v92
	v_add_u32_e32 v7, s8, v7
	s_nop 0
	v_addc_co_u32_e32 v93, vcc, 0, v93, vcc
	global_load_dword v115, v[94:95], off
	global_load_dword v116, v[92:93], off
	s_nop 0
	global_load_dwordx4 v[92:95], v[96:97], off nt
	s_nop 0
	global_load_dwordx4 v[96:99], v[96:97], off offset:2048 nt
	v_lshlrev_b64 v[100:101], 10, v[100:101]
	v_lshl_add_u64 v[100:101], v[4:5], 0, v[100:101]
	s_waitcnt vmcnt(6)
	v_lshlrev_b32_e32 v22, 16, v8
	v_and_b32_e32 v23, 0xffff0000, v8
	v_lshlrev_b32_e32 v8, 16, v9
	v_and_b32_e32 v9, 0xffff0000, v9
	v_lshlrev_b32_e32 v24, 16, v10
	v_max3_f32 v37, v34, v35, v36
	v_sub_f32_e32 v34, v34, v37
	v_sub_f32_e32 v35, v35, v37
	v_sub_f32_e32 v36, v36, v37
	v_mul_f32_e32 v34, 0x3fb8aa3b, v34
	v_mul_f32_e32 v35, 0x3fb8aa3b, v35
	v_mul_f32_e32 v36, 0x3fb8aa3b, v36
	v_exp_f32_e32 v37, v34
	v_exp_f32_e32 v35, v35
	v_exp_f32_e32 v34, v36
	v_and_b32_e32 v25, 0xffff0000, v10
	v_lshlrev_b32_e32 v10, 16, v11
	v_add_f32_e32 v36, v37, v35
	v_add_f32_e32 v36, v34, v36
	v_rcp_f32_e32 v38, v36
	v_and_b32_e32 v11, 0xffff0000, v11
	v_lshlrev_b32_e32 v30, 16, v12
	v_and_b32_e32 v31, 0xffff0000, v12
	v_mul_f32_e32 v36, v35, v38
	v_lshlrev_b32_e32 v12, 16, v13
	v_and_b32_e32 v13, 0xffff0000, v13
	v_lshlrev_b32_e32 v32, 16, v14
	v_and_b32_e32 v33, 0xffff0000, v14
	v_lshlrev_b32_e32 v14, 16, v15
	v_and_b32_e32 v15, 0xffff0000, v15
	v_mul_f32_e32 v34, v34, v38
	v_mul_f32_e32 v38, v37, v38
	v_pk_mul_f32 v[8:9], v[36:37], v[8:9] op_sel_hi:[0,1]
	v_pk_mul_f32 v[22:23], v[36:37], v[22:23] op_sel_hi:[0,1]
	v_pk_mul_f32 v[10:11], v[36:37], v[10:11] op_sel_hi:[0,1]
	v_pk_mul_f32 v[24:25], v[36:37], v[24:25] op_sel_hi:[0,1]
	v_lshlrev_b32_e32 v26, 16, v16
	v_and_b32_e32 v27, 0xffff0000, v16
	v_lshlrev_b32_e32 v16, 16, v17
	v_and_b32_e32 v17, 0xffff0000, v17
	v_lshlrev_b32_e32 v28, 16, v18
	v_and_b32_e32 v29, 0xffff0000, v18
	v_lshlrev_b32_e32 v18, 16, v19
	v_and_b32_e32 v19, 0xffff0000, v19
	v_pk_fma_f32 v[22:23], v[38:39], v[30:31], v[22:23] op_sel_hi:[0,1,1]
	v_pk_fma_f32 v[8:9], v[38:39], v[12:13], v[8:9] op_sel_hi:[0,1,1]
	v_pk_fma_f32 v[12:13], v[38:39], v[32:33], v[24:25] op_sel_hi:[0,1,1]
	v_pk_fma_f32 v[10:11], v[38:39], v[14:15], v[10:11] op_sel_hi:[0,1,1]
	v_pk_fma_f32 v[14:15], v[34:35], v[16:17], v[8:9] op_sel_hi:[0,1,1]
	v_pk_fma_f32 v[8:9], v[34:35], v[26:27], v[22:23] op_sel_hi:[0,1,1]
	v_pk_fma_f32 v[16:17], v[34:35], v[18:19], v[10:11] op_sel_hi:[0,1,1]
	v_pk_fma_f32 v[10:11], v[34:35], v[28:29], v[12:13] op_sel_hi:[0,1,1]
	v_cvt_pk_bf16_f32 v8, v8, v9
	v_cvt_pk_bf16_f32 v9, v14, v15
	v_cvt_pk_bf16_f32 v10, v10, v11
	v_cvt_pk_bf16_f32 v11, v16, v17
	global_store_dwordx4 v[20:21], v[8:11], off
	s_nop 1
	v_ashrrev_i32_e32 v20, 6, v7
	v_ashrrev_i32_e32 v21, 31, v20
	v_lshlrev_b64 v[12:13], 5, v[20:21]
	v_lshl_add_u64 v[12:13], s[34:35], 0, v[12:13]
	v_lshl_add_u64 v[12:13], v[12:13], 0, v[0:1]
	v_add_co_u32_e32 v14, vcc, 0x80000, v12
	v_mad_i64_i32 v[16:17], s[10:11], v20, s6, v[2:3]
	s_nop 0
	v_addc_co_u32_e32 v15, vcc, 0, v13, vcc
	global_load_dwordx4 v[8:11], v[16:17], off offset:1024 nt
	global_load_dword v34, v[12:13], off
	v_add_co_u32_e32 v12, vcc, 0x100000, v12
	v_add_u32_e32 v7, s8, v7
	s_nop 0
	v_addc_co_u32_e32 v13, vcc, 0, v13, vcc
	global_load_dword v35, v[14:15], off
	global_load_dword v36, v[12:13], off
	s_nop 0
	global_load_dwordx4 v[12:15], v[16:17], off nt
	s_nop 0
	global_load_dwordx4 v[16:19], v[16:17], off offset:2048 nt
	v_lshlrev_b64 v[20:21], 10, v[20:21]
	v_lshl_add_u64 v[20:21], v[4:5], 0, v[20:21]
	s_waitcnt vmcnt(7)
	v_lshlrev_b32_e32 v102, 16, v88
	v_and_b32_e32 v103, 0xffff0000, v88
	v_lshlrev_b32_e32 v88, 16, v89
	v_and_b32_e32 v89, 0xffff0000, v89
	v_lshlrev_b32_e32 v104, 16, v90
	v_max3_f32 v117, v114, v115, v116
	v_sub_f32_e32 v114, v114, v117
	v_sub_f32_e32 v115, v115, v117
	v_sub_f32_e32 v116, v116, v117
	v_mul_f32_e32 v114, 0x3fb8aa3b, v114
	v_mul_f32_e32 v115, 0x3fb8aa3b, v115
	v_mul_f32_e32 v116, 0x3fb8aa3b, v116
	v_exp_f32_e32 v117, v114
	v_exp_f32_e32 v115, v115
	v_exp_f32_e32 v114, v116
	v_and_b32_e32 v105, 0xffff0000, v90
	v_lshlrev_b32_e32 v90, 16, v91
	v_add_f32_e32 v116, v117, v115
	v_add_f32_e32 v116, v114, v116
	v_rcp_f32_e32 v118, v116
	v_and_b32_e32 v91, 0xffff0000, v91
	v_lshlrev_b32_e32 v110, 16, v92
	v_and_b32_e32 v111, 0xffff0000, v92
	v_mul_f32_e32 v116, v115, v118
	v_lshlrev_b32_e32 v92, 16, v93
	v_and_b32_e32 v93, 0xffff0000, v93
	v_lshlrev_b32_e32 v112, 16, v94
	v_and_b32_e32 v113, 0xffff0000, v94
	v_lshlrev_b32_e32 v94, 16, v95
	v_and_b32_e32 v95, 0xffff0000, v95
	v_mul_f32_e32 v114, v114, v118
	v_mul_f32_e32 v118, v117, v118
	v_pk_mul_f32 v[88:89], v[116:117], v[88:89] op_sel_hi:[0,1]
	v_pk_mul_f32 v[102:103], v[116:117], v[102:103] op_sel_hi:[0,1]
	v_pk_mul_f32 v[90:91], v[116:117], v[90:91] op_sel_hi:[0,1]
	v_pk_mul_f32 v[104:105], v[116:117], v[104:105] op_sel_hi:[0,1]
	v_lshlrev_b32_e32 v106, 16, v96
	v_and_b32_e32 v107, 0xffff0000, v96
	v_lshlrev_b32_e32 v96, 16, v97
	v_and_b32_e32 v97, 0xffff0000, v97
	v_lshlrev_b32_e32 v108, 16, v98
	v_and_b32_e32 v109, 0xffff0000, v98
	v_lshlrev_b32_e32 v98, 16, v99
	v_and_b32_e32 v99, 0xffff0000, v99
	v_pk_fma_f32 v[102:103], v[118:119], v[110:111], v[102:103] op_sel_hi:[0,1,1]
	v_pk_fma_f32 v[88:89], v[118:119], v[92:93], v[88:89] op_sel_hi:[0,1,1]
	v_pk_fma_f32 v[92:93], v[118:119], v[112:113], v[104:105] op_sel_hi:[0,1,1]
	v_pk_fma_f32 v[90:91], v[118:119], v[94:95], v[90:91] op_sel_hi:[0,1,1]
	v_pk_fma_f32 v[94:95], v[114:115], v[96:97], v[88:89] op_sel_hi:[0,1,1]
	v_pk_fma_f32 v[88:89], v[114:115], v[106:107], v[102:103] op_sel_hi:[0,1,1]
	v_pk_fma_f32 v[96:97], v[114:115], v[98:99], v[90:91] op_sel_hi:[0,1,1]
	v_pk_fma_f32 v[90:91], v[114:115], v[108:109], v[92:93] op_sel_hi:[0,1,1]
	v_cvt_pk_bf16_f32 v88, v88, v89
	v_cvt_pk_bf16_f32 v89, v94, v95
	v_cvt_pk_bf16_f32 v90, v90, v91
	v_cvt_pk_bf16_f32 v91, v96, v97
	global_store_dwordx4 v[100:101], v[88:91], off
	s_nop 1
	v_ashrrev_i32_e32 v100, 6, v7
	v_ashrrev_i32_e32 v101, 31, v100
	v_lshlrev_b64 v[92:93], 5, v[100:101]
	v_lshl_add_u64 v[92:93], s[34:35], 0, v[92:93]
	v_lshl_add_u64 v[92:93], v[92:93], 0, v[0:1]
	v_add_co_u32_e32 v94, vcc, 0x80000, v92
	v_mad_i64_i32 v[96:97], s[10:11], v100, s6, v[2:3]
	s_nop 0
	v_addc_co_u32_e32 v95, vcc, 0, v93, vcc
	global_load_dwordx4 v[88:91], v[96:97], off offset:1024 nt
	global_load_dword v114, v[92:93], off
	v_add_co_u32_e32 v92, vcc, 0x100000, v92
	v_add_u32_e32 v7, s8, v7
	s_nop 0
	v_addc_co_u32_e32 v93, vcc, 0, v93, vcc
	global_load_dword v115, v[94:95], off
	global_load_dword v116, v[92:93], off
	s_nop 0
	global_load_dwordx4 v[92:95], v[96:97], off nt
	s_nop 0
	global_load_dwordx4 v[96:99], v[96:97], off offset:2048 nt
	v_lshlrev_b64 v[100:101], 10, v[100:101]
	v_lshl_add_u64 v[100:101], v[4:5], 0, v[100:101]
	s_waitcnt vmcnt(7)
	v_lshlrev_b32_e32 v22, 16, v8
	v_and_b32_e32 v23, 0xffff0000, v8
	v_lshlrev_b32_e32 v8, 16, v9
	v_and_b32_e32 v9, 0xffff0000, v9
	v_lshlrev_b32_e32 v24, 16, v10
	v_max3_f32 v37, v34, v35, v36
	v_sub_f32_e32 v34, v34, v37
	v_sub_f32_e32 v35, v35, v37
	v_sub_f32_e32 v36, v36, v37
	v_mul_f32_e32 v34, 0x3fb8aa3b, v34
	v_mul_f32_e32 v35, 0x3fb8aa3b, v35
	v_mul_f32_e32 v36, 0x3fb8aa3b, v36
	v_exp_f32_e32 v37, v34
	v_exp_f32_e32 v35, v35
	v_exp_f32_e32 v34, v36
	v_and_b32_e32 v25, 0xffff0000, v10
	v_lshlrev_b32_e32 v10, 16, v11
	v_add_f32_e32 v36, v37, v35
	v_add_f32_e32 v36, v34, v36
	v_rcp_f32_e32 v38, v36
	v_and_b32_e32 v11, 0xffff0000, v11
	v_lshlrev_b32_e32 v30, 16, v12
	v_and_b32_e32 v31, 0xffff0000, v12
	v_mul_f32_e32 v36, v35, v38
	v_lshlrev_b32_e32 v12, 16, v13
	v_and_b32_e32 v13, 0xffff0000, v13
	v_lshlrev_b32_e32 v32, 16, v14
	v_and_b32_e32 v33, 0xffff0000, v14
	v_lshlrev_b32_e32 v14, 16, v15
	v_and_b32_e32 v15, 0xffff0000, v15
	v_mul_f32_e32 v34, v34, v38
	v_mul_f32_e32 v38, v37, v38
	v_pk_mul_f32 v[8:9], v[36:37], v[8:9] op_sel_hi:[0,1]
	v_pk_mul_f32 v[22:23], v[36:37], v[22:23] op_sel_hi:[0,1]
	v_pk_mul_f32 v[10:11], v[36:37], v[10:11] op_sel_hi:[0,1]
	v_pk_mul_f32 v[24:25], v[36:37], v[24:25] op_sel_hi:[0,1]
	v_lshlrev_b32_e32 v26, 16, v16
	v_and_b32_e32 v27, 0xffff0000, v16
	v_lshlrev_b32_e32 v16, 16, v17
	v_and_b32_e32 v17, 0xffff0000, v17
	v_lshlrev_b32_e32 v28, 16, v18
	v_and_b32_e32 v29, 0xffff0000, v18
	v_lshlrev_b32_e32 v18, 16, v19
	v_and_b32_e32 v19, 0xffff0000, v19
	v_pk_fma_f32 v[22:23], v[38:39], v[30:31], v[22:23] op_sel_hi:[0,1,1]
	v_pk_fma_f32 v[8:9], v[38:39], v[12:13], v[8:9] op_sel_hi:[0,1,1]
	v_pk_fma_f32 v[12:13], v[38:39], v[32:33], v[24:25] op_sel_hi:[0,1,1]
	v_pk_fma_f32 v[10:11], v[38:39], v[14:15], v[10:11] op_sel_hi:[0,1,1]
	v_pk_fma_f32 v[14:15], v[34:35], v[16:17], v[8:9] op_sel_hi:[0,1,1]
	v_pk_fma_f32 v[8:9], v[34:35], v[26:27], v[22:23] op_sel_hi:[0,1,1]
	v_pk_fma_f32 v[16:17], v[34:35], v[18:19], v[10:11] op_sel_hi:[0,1,1]
	v_pk_fma_f32 v[10:11], v[34:35], v[28:29], v[12:13] op_sel_hi:[0,1,1]
	v_cvt_pk_bf16_f32 v8, v8, v9
	v_cvt_pk_bf16_f32 v9, v14, v15
	v_cvt_pk_bf16_f32 v10, v10, v11
	v_cvt_pk_bf16_f32 v11, v16, v17
	global_store_dwordx4 v[20:21], v[8:11], off
	s_nop 1
	v_ashrrev_i32_e32 v20, 6, v7
	v_ashrrev_i32_e32 v21, 31, v20
	v_lshlrev_b64 v[12:13], 5, v[20:21]
	v_lshl_add_u64 v[12:13], s[34:35], 0, v[12:13]
	v_lshl_add_u64 v[12:13], v[12:13], 0, v[0:1]
	v_add_co_u32_e32 v14, vcc, 0x80000, v12
	v_mad_i64_i32 v[16:17], s[10:11], v20, s6, v[2:3]
	s_nop 0
	v_addc_co_u32_e32 v15, vcc, 0, v13, vcc
	global_load_dwordx4 v[8:11], v[16:17], off offset:1024 nt
	global_load_dword v34, v[12:13], off
	v_add_co_u32_e32 v12, vcc, 0x100000, v12
	v_add_u32_e32 v7, s8, v7
	s_nop 0
	v_addc_co_u32_e32 v13, vcc, 0, v13, vcc
	global_load_dword v35, v[14:15], off
	global_load_dword v36, v[12:13], off
	s_nop 0
	global_load_dwordx4 v[12:15], v[16:17], off nt
	s_nop 0
	global_load_dwordx4 v[16:19], v[16:17], off offset:2048 nt
	v_lshlrev_b64 v[20:21], 10, v[20:21]
	v_lshl_add_u64 v[20:21], v[4:5], 0, v[20:21]
	s_waitcnt vmcnt(7)
	v_lshlrev_b32_e32 v102, 16, v88
	v_and_b32_e32 v103, 0xffff0000, v88
	v_lshlrev_b32_e32 v88, 16, v89
	v_and_b32_e32 v89, 0xffff0000, v89
	v_lshlrev_b32_e32 v104, 16, v90
	v_max3_f32 v117, v114, v115, v116
	v_sub_f32_e32 v114, v114, v117
	v_sub_f32_e32 v115, v115, v117
	v_sub_f32_e32 v116, v116, v117
	v_mul_f32_e32 v114, 0x3fb8aa3b, v114
	v_mul_f32_e32 v115, 0x3fb8aa3b, v115
	v_mul_f32_e32 v116, 0x3fb8aa3b, v116
	v_exp_f32_e32 v117, v114
	v_exp_f32_e32 v115, v115
	v_exp_f32_e32 v114, v116
	v_and_b32_e32 v105, 0xffff0000, v90
	v_lshlrev_b32_e32 v90, 16, v91
	v_add_f32_e32 v116, v117, v115
	v_add_f32_e32 v116, v114, v116
	v_rcp_f32_e32 v118, v116
	v_and_b32_e32 v91, 0xffff0000, v91
	v_lshlrev_b32_e32 v110, 16, v92
	v_and_b32_e32 v111, 0xffff0000, v92
	v_mul_f32_e32 v116, v115, v118
	v_lshlrev_b32_e32 v92, 16, v93
	v_and_b32_e32 v93, 0xffff0000, v93
	v_lshlrev_b32_e32 v112, 16, v94
	v_and_b32_e32 v113, 0xffff0000, v94
	v_lshlrev_b32_e32 v94, 16, v95
	v_and_b32_e32 v95, 0xffff0000, v95
	v_mul_f32_e32 v114, v114, v118
	v_mul_f32_e32 v118, v117, v118
	v_pk_mul_f32 v[88:89], v[116:117], v[88:89] op_sel_hi:[0,1]
	v_pk_mul_f32 v[102:103], v[116:117], v[102:103] op_sel_hi:[0,1]
	v_pk_mul_f32 v[90:91], v[116:117], v[90:91] op_sel_hi:[0,1]
	v_pk_mul_f32 v[104:105], v[116:117], v[104:105] op_sel_hi:[0,1]
	v_lshlrev_b32_e32 v106, 16, v96
	v_and_b32_e32 v107, 0xffff0000, v96
	v_lshlrev_b32_e32 v96, 16, v97
	v_and_b32_e32 v97, 0xffff0000, v97
	v_lshlrev_b32_e32 v108, 16, v98
	v_and_b32_e32 v109, 0xffff0000, v98
	v_lshlrev_b32_e32 v98, 16, v99
	v_and_b32_e32 v99, 0xffff0000, v99
	v_pk_fma_f32 v[102:103], v[118:119], v[110:111], v[102:103] op_sel_hi:[0,1,1]
	v_pk_fma_f32 v[88:89], v[118:119], v[92:93], v[88:89] op_sel_hi:[0,1,1]
	v_pk_fma_f32 v[92:93], v[118:119], v[112:113], v[104:105] op_sel_hi:[0,1,1]
	v_pk_fma_f32 v[90:91], v[118:119], v[94:95], v[90:91] op_sel_hi:[0,1,1]
	v_pk_fma_f32 v[94:95], v[114:115], v[96:97], v[88:89] op_sel_hi:[0,1,1]
	v_pk_fma_f32 v[88:89], v[114:115], v[106:107], v[102:103] op_sel_hi:[0,1,1]
	v_pk_fma_f32 v[96:97], v[114:115], v[98:99], v[90:91] op_sel_hi:[0,1,1]
	v_pk_fma_f32 v[90:91], v[114:115], v[108:109], v[92:93] op_sel_hi:[0,1,1]
	v_cvt_pk_bf16_f32 v88, v88, v89
	v_cvt_pk_bf16_f32 v89, v94, v95
	v_cvt_pk_bf16_f32 v90, v90, v91
	v_cvt_pk_bf16_f32 v91, v96, v97
	global_store_dwordx4 v[100:101], v[88:91], off
	s_nop 1
	v_ashrrev_i32_e32 v100, 6, v7
	v_ashrrev_i32_e32 v101, 31, v100
	v_lshlrev_b64 v[92:93], 5, v[100:101]
	v_lshl_add_u64 v[92:93], s[34:35], 0, v[92:93]
	v_lshl_add_u64 v[92:93], v[92:93], 0, v[0:1]
	v_add_co_u32_e32 v94, vcc, 0x80000, v92
	v_mad_i64_i32 v[96:97], s[10:11], v100, s6, v[2:3]
	s_nop 0
	v_addc_co_u32_e32 v95, vcc, 0, v93, vcc
	global_load_dwordx4 v[88:91], v[96:97], off offset:1024 nt
	global_load_dword v114, v[92:93], off
	v_add_co_u32_e32 v92, vcc, 0x100000, v92
	v_add_u32_e32 v7, s8, v7
	s_nop 0
	v_addc_co_u32_e32 v93, vcc, 0, v93, vcc
	global_load_dword v115, v[94:95], off
	global_load_dword v116, v[92:93], off
	s_nop 0
	global_load_dwordx4 v[92:95], v[96:97], off nt
	s_nop 0
	global_load_dwordx4 v[96:99], v[96:97], off offset:2048 nt
	v_lshlrev_b64 v[100:101], 10, v[100:101]
	v_lshl_add_u64 v[100:101], v[4:5], 0, v[100:101]
	s_waitcnt vmcnt(7)
	v_lshlrev_b32_e32 v22, 16, v8
	v_and_b32_e32 v23, 0xffff0000, v8
	v_lshlrev_b32_e32 v8, 16, v9
	v_and_b32_e32 v9, 0xffff0000, v9
	v_lshlrev_b32_e32 v24, 16, v10
	v_max3_f32 v37, v34, v35, v36
	v_sub_f32_e32 v34, v34, v37
	v_sub_f32_e32 v35, v35, v37
	v_sub_f32_e32 v36, v36, v37
	v_mul_f32_e32 v34, 0x3fb8aa3b, v34
	v_mul_f32_e32 v35, 0x3fb8aa3b, v35
	v_mul_f32_e32 v36, 0x3fb8aa3b, v36
	v_exp_f32_e32 v37, v34
	v_exp_f32_e32 v35, v35
	v_exp_f32_e32 v34, v36
	v_and_b32_e32 v25, 0xffff0000, v10
	v_lshlrev_b32_e32 v10, 16, v11
	v_add_f32_e32 v36, v37, v35
	v_add_f32_e32 v36, v34, v36
	v_rcp_f32_e32 v38, v36
	v_and_b32_e32 v11, 0xffff0000, v11
	v_lshlrev_b32_e32 v30, 16, v12
	v_and_b32_e32 v31, 0xffff0000, v12
	v_mul_f32_e32 v36, v35, v38
	v_lshlrev_b32_e32 v12, 16, v13
	v_and_b32_e32 v13, 0xffff0000, v13
	v_lshlrev_b32_e32 v32, 16, v14
	v_and_b32_e32 v33, 0xffff0000, v14
	v_lshlrev_b32_e32 v14, 16, v15
	v_and_b32_e32 v15, 0xffff0000, v15
	v_mul_f32_e32 v34, v34, v38
	v_mul_f32_e32 v38, v37, v38
	v_pk_mul_f32 v[8:9], v[36:37], v[8:9] op_sel_hi:[0,1]
	v_pk_mul_f32 v[22:23], v[36:37], v[22:23] op_sel_hi:[0,1]
	v_pk_mul_f32 v[10:11], v[36:37], v[10:11] op_sel_hi:[0,1]
	v_pk_mul_f32 v[24:25], v[36:37], v[24:25] op_sel_hi:[0,1]
	v_lshlrev_b32_e32 v26, 16, v16
	v_and_b32_e32 v27, 0xffff0000, v16
	v_lshlrev_b32_e32 v16, 16, v17
	v_and_b32_e32 v17, 0xffff0000, v17
	v_lshlrev_b32_e32 v28, 16, v18
	v_and_b32_e32 v29, 0xffff0000, v18
	v_lshlrev_b32_e32 v18, 16, v19
	v_and_b32_e32 v19, 0xffff0000, v19
	v_pk_fma_f32 v[22:23], v[38:39], v[30:31], v[22:23] op_sel_hi:[0,1,1]
	v_pk_fma_f32 v[8:9], v[38:39], v[12:13], v[8:9] op_sel_hi:[0,1,1]
	v_pk_fma_f32 v[12:13], v[38:39], v[32:33], v[24:25] op_sel_hi:[0,1,1]
	v_pk_fma_f32 v[10:11], v[38:39], v[14:15], v[10:11] op_sel_hi:[0,1,1]
	v_pk_fma_f32 v[14:15], v[34:35], v[16:17], v[8:9] op_sel_hi:[0,1,1]
	v_pk_fma_f32 v[8:9], v[34:35], v[26:27], v[22:23] op_sel_hi:[0,1,1]
	v_pk_fma_f32 v[16:17], v[34:35], v[18:19], v[10:11] op_sel_hi:[0,1,1]
	v_pk_fma_f32 v[10:11], v[34:35], v[28:29], v[12:13] op_sel_hi:[0,1,1]
	v_cvt_pk_bf16_f32 v8, v8, v9
	v_cvt_pk_bf16_f32 v9, v14, v15
	v_cvt_pk_bf16_f32 v10, v10, v11
	v_cvt_pk_bf16_f32 v11, v16, v17
	global_store_dwordx4 v[20:21], v[8:11], off
	s_nop 1
	v_ashrrev_i32_e32 v20, 6, v7
	v_ashrrev_i32_e32 v21, 31, v20
	v_lshlrev_b64 v[12:13], 5, v[20:21]
	v_lshl_add_u64 v[12:13], s[34:35], 0, v[12:13]
	v_lshl_add_u64 v[12:13], v[12:13], 0, v[0:1]
	v_add_co_u32_e32 v14, vcc, 0x80000, v12
	v_mad_i64_i32 v[16:17], s[10:11], v20, s6, v[2:3]
	s_nop 0
	v_addc_co_u32_e32 v15, vcc, 0, v13, vcc
	global_load_dwordx4 v[8:11], v[16:17], off offset:1024 nt
	global_load_dword v34, v[12:13], off
	v_add_co_u32_e32 v12, vcc, 0x100000, v12
	v_add_u32_e32 v7, s8, v7
	s_nop 0
	v_addc_co_u32_e32 v13, vcc, 0, v13, vcc
	global_load_dword v35, v[14:15], off
	global_load_dword v36, v[12:13], off
	s_nop 0
	global_load_dwordx4 v[12:15], v[16:17], off nt
	s_nop 0
	global_load_dwordx4 v[16:19], v[16:17], off offset:2048 nt
	v_lshlrev_b64 v[20:21], 10, v[20:21]
	v_lshl_add_u64 v[20:21], v[4:5], 0, v[20:21]
	s_waitcnt vmcnt(7)
	v_lshlrev_b32_e32 v102, 16, v88
	v_and_b32_e32 v103, 0xffff0000, v88
	v_lshlrev_b32_e32 v88, 16, v89
	v_and_b32_e32 v89, 0xffff0000, v89
	v_lshlrev_b32_e32 v104, 16, v90
	v_max3_f32 v117, v114, v115, v116
	v_sub_f32_e32 v114, v114, v117
	v_sub_f32_e32 v115, v115, v117
	v_sub_f32_e32 v116, v116, v117
	v_mul_f32_e32 v114, 0x3fb8aa3b, v114
	v_mul_f32_e32 v115, 0x3fb8aa3b, v115
	v_mul_f32_e32 v116, 0x3fb8aa3b, v116
	v_exp_f32_e32 v117, v114
	v_exp_f32_e32 v115, v115
	v_exp_f32_e32 v114, v116
	v_and_b32_e32 v105, 0xffff0000, v90
	v_lshlrev_b32_e32 v90, 16, v91
	v_add_f32_e32 v116, v117, v115
	v_add_f32_e32 v116, v114, v116
	v_rcp_f32_e32 v118, v116
	v_and_b32_e32 v91, 0xffff0000, v91
	v_lshlrev_b32_e32 v110, 16, v92
	v_and_b32_e32 v111, 0xffff0000, v92
	v_mul_f32_e32 v116, v115, v118
	v_lshlrev_b32_e32 v92, 16, v93
	v_and_b32_e32 v93, 0xffff0000, v93
	v_lshlrev_b32_e32 v112, 16, v94
	v_and_b32_e32 v113, 0xffff0000, v94
	v_lshlrev_b32_e32 v94, 16, v95
	v_and_b32_e32 v95, 0xffff0000, v95
	v_mul_f32_e32 v114, v114, v118
	v_mul_f32_e32 v118, v117, v118
	v_pk_mul_f32 v[88:89], v[116:117], v[88:89] op_sel_hi:[0,1]
	v_pk_mul_f32 v[102:103], v[116:117], v[102:103] op_sel_hi:[0,1]
	v_pk_mul_f32 v[90:91], v[116:117], v[90:91] op_sel_hi:[0,1]
	v_pk_mul_f32 v[104:105], v[116:117], v[104:105] op_sel_hi:[0,1]
	v_lshlrev_b32_e32 v106, 16, v96
	v_and_b32_e32 v107, 0xffff0000, v96
	v_lshlrev_b32_e32 v96, 16, v97
	v_and_b32_e32 v97, 0xffff0000, v97
	v_lshlrev_b32_e32 v108, 16, v98
	v_and_b32_e32 v109, 0xffff0000, v98
	v_lshlrev_b32_e32 v98, 16, v99
	v_and_b32_e32 v99, 0xffff0000, v99
	v_pk_fma_f32 v[102:103], v[118:119], v[110:111], v[102:103] op_sel_hi:[0,1,1]
	v_pk_fma_f32 v[88:89], v[118:119], v[92:93], v[88:89] op_sel_hi:[0,1,1]
	v_pk_fma_f32 v[92:93], v[118:119], v[112:113], v[104:105] op_sel_hi:[0,1,1]
	v_pk_fma_f32 v[90:91], v[118:119], v[94:95], v[90:91] op_sel_hi:[0,1,1]
	v_pk_fma_f32 v[94:95], v[114:115], v[96:97], v[88:89] op_sel_hi:[0,1,1]
	v_pk_fma_f32 v[88:89], v[114:115], v[106:107], v[102:103] op_sel_hi:[0,1,1]
	v_pk_fma_f32 v[96:97], v[114:115], v[98:99], v[90:91] op_sel_hi:[0,1,1]
	v_pk_fma_f32 v[90:91], v[114:115], v[108:109], v[92:93] op_sel_hi:[0,1,1]
	v_cvt_pk_bf16_f32 v88, v88, v89
	v_cvt_pk_bf16_f32 v89, v94, v95
	v_cvt_pk_bf16_f32 v90, v90, v91
	v_cvt_pk_bf16_f32 v91, v96, v97
	global_store_dwordx4 v[100:101], v[88:91], off
	s_nop 1
	v_ashrrev_i32_e32 v100, 6, v7
	v_ashrrev_i32_e32 v101, 31, v100
	v_lshlrev_b64 v[92:93], 5, v[100:101]
	v_lshl_add_u64 v[92:93], s[34:35], 0, v[92:93]
	v_lshl_add_u64 v[92:93], v[92:93], 0, v[0:1]
	v_add_co_u32_e32 v94, vcc, 0x80000, v92
	v_mad_i64_i32 v[96:97], s[10:11], v100, s6, v[2:3]
	s_nop 0
	v_addc_co_u32_e32 v95, vcc, 0, v93, vcc
	global_load_dwordx4 v[88:91], v[96:97], off offset:1024 nt
	global_load_dword v114, v[92:93], off
	v_add_co_u32_e32 v92, vcc, 0x100000, v92
	v_add_u32_e32 v7, s8, v7
	s_nop 0
	v_addc_co_u32_e32 v93, vcc, 0, v93, vcc
	global_load_dword v115, v[94:95], off
	global_load_dword v116, v[92:93], off
	s_nop 0
	global_load_dwordx4 v[92:95], v[96:97], off nt
	s_nop 0
	global_load_dwordx4 v[96:99], v[96:97], off offset:2048 nt
	v_lshlrev_b64 v[100:101], 10, v[100:101]
	v_lshl_add_u64 v[100:101], v[4:5], 0, v[100:101]
	s_waitcnt vmcnt(7)
	v_lshlrev_b32_e32 v22, 16, v8
	v_and_b32_e32 v23, 0xffff0000, v8
	v_lshlrev_b32_e32 v8, 16, v9
	v_and_b32_e32 v9, 0xffff0000, v9
	v_lshlrev_b32_e32 v24, 16, v10
	v_max3_f32 v37, v34, v35, v36
	v_sub_f32_e32 v34, v34, v37
	v_sub_f32_e32 v35, v35, v37
	v_sub_f32_e32 v36, v36, v37
	v_mul_f32_e32 v34, 0x3fb8aa3b, v34
	v_mul_f32_e32 v35, 0x3fb8aa3b, v35
	v_mul_f32_e32 v36, 0x3fb8aa3b, v36
	v_exp_f32_e32 v37, v34
	v_exp_f32_e32 v35, v35
	v_exp_f32_e32 v34, v36
	v_and_b32_e32 v25, 0xffff0000, v10
	v_lshlrev_b32_e32 v10, 16, v11
	v_add_f32_e32 v36, v37, v35
	v_add_f32_e32 v36, v34, v36
	v_rcp_f32_e32 v38, v36
	v_and_b32_e32 v11, 0xffff0000, v11
	v_lshlrev_b32_e32 v30, 16, v12
	v_and_b32_e32 v31, 0xffff0000, v12
	v_mul_f32_e32 v36, v35, v38
	v_lshlrev_b32_e32 v12, 16, v13
	v_and_b32_e32 v13, 0xffff0000, v13
	v_lshlrev_b32_e32 v32, 16, v14
	v_and_b32_e32 v33, 0xffff0000, v14
	v_lshlrev_b32_e32 v14, 16, v15
	v_and_b32_e32 v15, 0xffff0000, v15
	v_mul_f32_e32 v34, v34, v38
	v_mul_f32_e32 v38, v37, v38
	v_pk_mul_f32 v[8:9], v[36:37], v[8:9] op_sel_hi:[0,1]
	v_pk_mul_f32 v[22:23], v[36:37], v[22:23] op_sel_hi:[0,1]
	v_pk_mul_f32 v[10:11], v[36:37], v[10:11] op_sel_hi:[0,1]
	v_pk_mul_f32 v[24:25], v[36:37], v[24:25] op_sel_hi:[0,1]
	v_lshlrev_b32_e32 v26, 16, v16
	v_and_b32_e32 v27, 0xffff0000, v16
	v_lshlrev_b32_e32 v16, 16, v17
	v_and_b32_e32 v17, 0xffff0000, v17
	v_lshlrev_b32_e32 v28, 16, v18
	v_and_b32_e32 v29, 0xffff0000, v18
	v_lshlrev_b32_e32 v18, 16, v19
	v_and_b32_e32 v19, 0xffff0000, v19
	v_pk_fma_f32 v[22:23], v[38:39], v[30:31], v[22:23] op_sel_hi:[0,1,1]
	v_pk_fma_f32 v[8:9], v[38:39], v[12:13], v[8:9] op_sel_hi:[0,1,1]
	v_pk_fma_f32 v[12:13], v[38:39], v[32:33], v[24:25] op_sel_hi:[0,1,1]
	v_pk_fma_f32 v[10:11], v[38:39], v[14:15], v[10:11] op_sel_hi:[0,1,1]
	v_pk_fma_f32 v[14:15], v[34:35], v[16:17], v[8:9] op_sel_hi:[0,1,1]
	v_pk_fma_f32 v[8:9], v[34:35], v[26:27], v[22:23] op_sel_hi:[0,1,1]
	v_pk_fma_f32 v[16:17], v[34:35], v[18:19], v[10:11] op_sel_hi:[0,1,1]
	v_pk_fma_f32 v[10:11], v[34:35], v[28:29], v[12:13] op_sel_hi:[0,1,1]
	v_cvt_pk_bf16_f32 v8, v8, v9
	v_cvt_pk_bf16_f32 v9, v14, v15
	v_cvt_pk_bf16_f32 v10, v10, v11
	v_cvt_pk_bf16_f32 v11, v16, v17
	global_store_dwordx4 v[20:21], v[8:11], off
	s_nop 1
	s_waitcnt vmcnt(1)
	v_lshlrev_b32_e32 v102, 16, v88
	v_and_b32_e32 v103, 0xffff0000, v88
	v_lshlrev_b32_e32 v88, 16, v89
	v_and_b32_e32 v89, 0xffff0000, v89
	v_lshlrev_b32_e32 v104, 16, v90
	v_max3_f32 v117, v114, v115, v116
	v_sub_f32_e32 v114, v114, v117
	v_sub_f32_e32 v115, v115, v117
	v_sub_f32_e32 v116, v116, v117
	v_mul_f32_e32 v114, 0x3fb8aa3b, v114
	v_mul_f32_e32 v115, 0x3fb8aa3b, v115
	v_mul_f32_e32 v116, 0x3fb8aa3b, v116
	v_exp_f32_e32 v117, v114
	v_exp_f32_e32 v115, v115
	v_exp_f32_e32 v114, v116
	v_and_b32_e32 v105, 0xffff0000, v90
	v_lshlrev_b32_e32 v90, 16, v91
	v_add_f32_e32 v116, v117, v115
	v_add_f32_e32 v116, v114, v116
	v_rcp_f32_e32 v118, v116
	v_and_b32_e32 v91, 0xffff0000, v91
	v_lshlrev_b32_e32 v110, 16, v92
	v_and_b32_e32 v111, 0xffff0000, v92
	v_mul_f32_e32 v116, v115, v118
	v_lshlrev_b32_e32 v92, 16, v93
	v_and_b32_e32 v93, 0xffff0000, v93
	v_lshlrev_b32_e32 v112, 16, v94
	v_and_b32_e32 v113, 0xffff0000, v94
	v_lshlrev_b32_e32 v94, 16, v95
	v_and_b32_e32 v95, 0xffff0000, v95
	v_mul_f32_e32 v114, v114, v118
	v_mul_f32_e32 v118, v117, v118
	v_pk_mul_f32 v[88:89], v[116:117], v[88:89] op_sel_hi:[0,1]
	v_pk_mul_f32 v[102:103], v[116:117], v[102:103] op_sel_hi:[0,1]
	v_pk_mul_f32 v[90:91], v[116:117], v[90:91] op_sel_hi:[0,1]
	v_pk_mul_f32 v[104:105], v[116:117], v[104:105] op_sel_hi:[0,1]
	v_lshlrev_b32_e32 v106, 16, v96
	v_and_b32_e32 v107, 0xffff0000, v96
	v_lshlrev_b32_e32 v96, 16, v97
	v_and_b32_e32 v97, 0xffff0000, v97
	v_lshlrev_b32_e32 v108, 16, v98
	v_and_b32_e32 v109, 0xffff0000, v98
	v_lshlrev_b32_e32 v98, 16, v99
	v_and_b32_e32 v99, 0xffff0000, v99
	v_pk_fma_f32 v[102:103], v[118:119], v[110:111], v[102:103] op_sel_hi:[0,1,1]
	v_pk_fma_f32 v[88:89], v[118:119], v[92:93], v[88:89] op_sel_hi:[0,1,1]
	v_pk_fma_f32 v[92:93], v[118:119], v[112:113], v[104:105] op_sel_hi:[0,1,1]
	v_pk_fma_f32 v[90:91], v[118:119], v[94:95], v[90:91] op_sel_hi:[0,1,1]
	v_pk_fma_f32 v[94:95], v[114:115], v[96:97], v[88:89] op_sel_hi:[0,1,1]
	v_pk_fma_f32 v[88:89], v[114:115], v[106:107], v[102:103] op_sel_hi:[0,1,1]
	v_pk_fma_f32 v[96:97], v[114:115], v[98:99], v[90:91] op_sel_hi:[0,1,1]
	v_pk_fma_f32 v[90:91], v[114:115], v[108:109], v[92:93] op_sel_hi:[0,1,1]
	v_cvt_pk_bf16_f32 v88, v88, v89
	v_cvt_pk_bf16_f32 v89, v94, v95
	v_cvt_pk_bf16_f32 v90, v90, v91
	v_cvt_pk_bf16_f32 v91, v96, v97
	global_store_dwordx4 v[100:101], v[88:91], off
	s_nop 1
	s_branch .LBB0_584

.LBB0_584:
	s_or_b64 exec, exec, s[0:1]
	s_and_b64 s[0:1], s[92:93], exec
	s_cselect_b32 s0, 0x180000, 0
	v_add_u32_e32 v0, s0, v6
	s_mov_b32 s0, 0x200000
	v_cmp_gt_i32_e32 vcc, s0, v0
	s_and_saveexec_b64 s[0:1], vcc
	s_cbranch_execz .LBB0_587
	v_mbcnt_lo_u32_b32 v1, -1, 0
	v_mbcnt_hi_u32_b32 v4, -1, v1
	v_and_b32_e32 v2, 64, v4
	v_xor_b32_e32 v1, 1, v4
	v_add_u32_e32 v5, 64, v2
	v_cmp_lt_i32_e32 vcc, v1, v5
	v_xor_b32_e32 v2, 2, v4
	v_xor_b32_e32 v3, 4, v4
	v_cndmask_b32_e32 v1, v4, v1, vcc
	v_cmp_lt_i32_e32 vcc, v2, v5
	v_xor_b32_e32 v6, 8, v4
	v_readlane_b32 s6, v246, 48
	v_cndmask_b32_e32 v2, v4, v2, vcc
	v_cmp_lt_i32_e32 vcc, v3, v5
	s_add_u32 s4, s76, 0xe000000
	v_readlane_b32 s7, v246, 49
	v_cndmask_b32_e32 v3, v4, v3, vcc
	v_cmp_lt_i32_e32 vcc, v6, v5
	s_addc_u32 s5, s77, 0
	v_lshlrev_b32_e32 v1, 2, v1
	v_cndmask_b32_e32 v4, v4, v6, vcc
	v_lshlrev_b32_e32 v2, 2, v2
	v_lshlrev_b32_e32 v3, 2, v3
	v_lshlrev_b32_e32 v4, 2, v4
	v_lshlrev_b32_e32 v5, 3, v0
	s_lshl_b32 s9, s6, 12
	s_mov_b64 s[6:7], 0
	v_mov_b32_e32 v6, 0x358637bd
	s_mov_b32 s10, 0x1fffff
	s_and_b64 vcc, exec, s[92:93]
	s_cbranch_vccz .LBB0_586
	v_ashrrev_i32_e32 v8, 7, v0
	v_ashrrev_i32_e32 v9, 31, v8
	v_and_b32_e32 v7, 0x3f8, v5
	v_lshlrev_b64 v[16:17], 11, v[8:9]
	v_and_b32_e32 v10, 0x78, v5
	v_lshl_or_b32 v16, v7, 1, v16
	v_lshlrev_b32_e32 v12, 2, v10
	v_lshl_add_u64 v[28:29], s[72:73], 0, v[16:17]
	v_lshl_add_u64 v[20:21], s[4:5], 0, v[16:17]
	v_lshl_add_u64 v[24:25], s[88:89], 0, v[16:17]
	global_load_dwordx4 v[8:11], v12, s[54:55] offset:16
	s_nop 0
	global_load_dwordx4 v[12:15], v12, s[54:55]
	s_nop 0
	global_load_dwordx4 v[16:19], v[28:29], off nt
	s_nop 0
	global_load_dwordx4 v[20:23], v[20:21], off nt
	s_nop 0
	global_load_dwordx4 v[24:27], v[24:25], off nt
	v_add_u32_e32 v0, s8, v0
	v_add_u32_e32 v5, s9, v5
	v_ashrrev_i32_e32 v88, 7, v0
	v_ashrrev_i32_e32 v89, 31, v88
	v_and_b32_e32 v87, 0x3f8, v5
	v_lshlrev_b64 v[96:97], 11, v[88:89]
	v_and_b32_e32 v90, 0x78, v5
	v_lshl_or_b32 v96, v87, 1, v96
	v_lshlrev_b32_e32 v92, 2, v90
	v_lshl_add_u64 v[108:109], s[72:73], 0, v[96:97]
	v_lshl_add_u64 v[100:101], s[4:5], 0, v[96:97]
	v_lshl_add_u64 v[104:105], s[88:89], 0, v[96:97]
	global_load_dwordx4 v[88:91], v92, s[54:55] offset:16
	s_nop 0
	global_load_dwordx4 v[92:95], v92, s[54:55]
	s_nop 0
	global_load_dwordx4 v[96:99], v[108:109], off nt
	s_nop 0
	global_load_dwordx4 v[100:103], v[100:101], off nt
	s_nop 0
	global_load_dwordx4 v[104:107], v[104:105], off nt
	v_add_u32_e32 v0, s8, v0
	v_add_u32_e32 v5, s9, v5
	s_waitcnt vmcnt(5)
	v_lshlrev_b32_e32 v30, 16, v16
	v_and_b32_e32 v31, 0xffff0000, v16
	v_lshlrev_b32_e32 v16, 16, v17
	v_and_b32_e32 v17, 0xffff0000, v17
	v_lshlrev_b32_e32 v34, 16, v20
	v_and_b32_e32 v35, 0xffff0000, v20
	v_lshlrev_b32_e32 v20, 16, v21
	v_and_b32_e32 v21, 0xffff0000, v21
	v_lshlrev_b32_e32 v32, 16, v18
	v_and_b32_e32 v33, 0xffff0000, v18
	v_lshlrev_b32_e32 v18, 16, v19
	v_and_b32_e32 v19, 0xffff0000, v19
	v_lshlrev_b32_e32 v36, 16, v22
	v_and_b32_e32 v37, 0xffff0000, v22
	v_lshlrev_b32_e32 v22, 16, v23
	v_and_b32_e32 v23, 0xffff0000, v23
	v_pk_add_f32 v[30:31], v[30:31], v[34:35]
	v_pk_add_f32 v[16:17], v[16:17], v[20:21]
	v_pk_add_f32 v[20:21], v[32:33], v[36:37]
	v_pk_add_f32 v[18:19], v[18:19], v[22:23]
	v_pk_mul_f32 v[22:23], v[16:17], v[16:17]
	v_pk_mul_f32 v[32:33], v[30:31], v[30:31]
	v_pk_mul_f32 v[34:35], v[18:19], v[18:19]
	v_pk_mul_f32 v[36:37], v[20:21], v[20:21]
	v_pk_mov_b32 v[42:43], v[32:33], v[22:23] op_sel:[1,0]
	v_mov_b32_e32 v33, v23
	v_mov_b32_e32 v22, v34
	v_mov_b32_e32 v23, v36
	v_mov_b32_e32 v36, v35
	v_pk_add_f32 v[32:33], v[42:43], v[32:33]
	v_pk_add_f32 v[22:23], v[22:23], v[36:37]
	v_add_f32_e32 v7, v32, v33
	v_add_f32_e32 v7, v23, v7
	v_add_f32_e32 v7, v22, v7
	ds_bpermute_b32 v22, v1, v7
	v_lshlrev_b32_e32 v38, 16, v24
	v_and_b32_e32 v39, 0xffff0000, v24
	v_lshlrev_b32_e32 v24, 16, v25
	v_and_b32_e32 v25, 0xffff0000, v25
	s_waitcnt lgkmcnt(0)
	v_add_f32_e32 v7, v7, v22
	ds_bpermute_b32 v22, v2, v7
	v_lshlrev_b32_e32 v40, 16, v26
	v_and_b32_e32 v41, 0xffff0000, v26
	v_lshlrev_b32_e32 v26, 16, v27
	v_and_b32_e32 v27, 0xffff0000, v27
	s_waitcnt lgkmcnt(0)
	v_add_f32_e32 v7, v7, v22
	ds_bpermute_b32 v22, v3, v7
	s_waitcnt lgkmcnt(0)
	v_add_f32_e32 v7, v7, v22
	ds_bpermute_b32 v22, v4, v7
	s_waitcnt lgkmcnt(0)
	v_add_f32_e32 v7, v7, v22
	v_fmamk_f32 v7, v7, 0x3c000000, v6
	v_rsq_f32_e32 v22, v7
	s_nop 0
	v_pk_mul_f32 v[16:17], v[16:17], v[22:23] op_sel_hi:[1,0]
	v_pk_mul_f32 v[30:31], v[30:31], v[22:23] op_sel_hi:[1,0]
	v_pk_mul_f32 v[18:19], v[18:19], v[22:23] op_sel_hi:[1,0]
	v_pk_mul_f32 v[20:21], v[20:21], v[22:23] op_sel_hi:[1,0]
	v_pk_mul_f32 v[12:13], v[12:13], v[30:31]
	v_pk_mul_f32 v[14:15], v[14:15], v[16:17]
	v_pk_mul_f32 v[8:9], v[8:9], v[20:21]
	v_pk_mul_f32 v[10:11], v[10:11], v[18:19]
	v_pk_mul_f32 v[14:15], v[14:15], v[24:25]
	v_pk_mul_f32 v[12:13], v[12:13], v[38:39]
	v_pk_mul_f32 v[16:17], v[10:11], v[26:27]
	v_pk_mul_f32 v[10:11], v[8:9], v[40:41]
	v_cvt_pk_bf16_f32 v8, v12, v13
	v_cvt_pk_bf16_f32 v9, v14, v15
	v_cvt_pk_bf16_f32 v10, v10, v11
	v_cvt_pk_bf16_f32 v11, v16, v17
	global_store_dwordx4 v[28:29], v[8:11], off
	s_nop 1
	v_ashrrev_i32_e32 v8, 7, v0
	v_ashrrev_i32_e32 v9, 31, v8
	v_and_b32_e32 v7, 0x3f8, v5
	v_lshlrev_b64 v[16:17], 11, v[8:9]
	v_and_b32_e32 v10, 0x78, v5
	v_lshl_or_b32 v16, v7, 1, v16
	v_lshlrev_b32_e32 v12, 2, v10
	v_lshl_add_u64 v[28:29], s[72:73], 0, v[16:17]
	v_lshl_add_u64 v[20:21], s[4:5], 0, v[16:17]
	v_lshl_add_u64 v[24:25], s[88:89], 0, v[16:17]
	global_load_dwordx4 v[8:11], v12, s[54:55] offset:16
	s_nop 0
	global_load_dwordx4 v[12:15], v12, s[54:55]
	s_nop 0
	global_load_dwordx4 v[16:19], v[28:29], off nt
	s_nop 0
	global_load_dwordx4 v[20:23], v[20:21], off nt
	s_nop 0
	global_load_dwordx4 v[24:27], v[24:25], off nt
	v_add_u32_e32 v0, s8, v0
	v_add_u32_e32 v5, s9, v5
	s_waitcnt vmcnt(6)
	v_lshlrev_b32_e32 v110, 16, v96
	v_and_b32_e32 v111, 0xffff0000, v96
	v_lshlrev_b32_e32 v96, 16, v97
	v_and_b32_e32 v97, 0xffff0000, v97
	v_lshlrev_b32_e32 v114, 16, v100
	v_and_b32_e32 v115, 0xffff0000, v100
	v_lshlrev_b32_e32 v100, 16, v101
	v_and_b32_e32 v101, 0xffff0000, v101
	v_lshlrev_b32_e32 v112, 16, v98
	v_and_b32_e32 v113, 0xffff0000, v98
	v_lshlrev_b32_e32 v98, 16, v99
	v_and_b32_e32 v99, 0xffff0000, v99
	v_lshlrev_b32_e32 v116, 16, v102
	v_and_b32_e32 v117, 0xffff0000, v102
	v_lshlrev_b32_e32 v102, 16, v103
	v_and_b32_e32 v103, 0xffff0000, v103
	v_pk_add_f32 v[110:111], v[110:111], v[114:115]
	v_pk_add_f32 v[96:97], v[96:97], v[100:101]
	v_pk_add_f32 v[100:101], v[112:113], v[116:117]
	v_pk_add_f32 v[98:99], v[98:99], v[102:103]
	v_pk_mul_f32 v[102:103], v[96:97], v[96:97]
	v_pk_mul_f32 v[112:113], v[110:111], v[110:111]
	v_pk_mul_f32 v[114:115], v[98:99], v[98:99]
	v_pk_mul_f32 v[116:117], v[100:101], v[100:101]
	v_pk_mov_b32 v[122:123], v[112:113], v[102:103] op_sel:[1,0]
	v_mov_b32_e32 v113, v103
	v_mov_b32_e32 v102, v114
	v_mov_b32_e32 v103, v116
	v_mov_b32_e32 v116, v115
	v_pk_add_f32 v[112:113], v[122:123], v[112:113]
	v_pk_add_f32 v[102:103], v[102:103], v[116:117]
	v_add_f32_e32 v87, v112, v113
	v_add_f32_e32 v87, v103, v87
	v_add_f32_e32 v87, v102, v87
	ds_bpermute_b32 v102, v1, v87
	v_lshlrev_b32_e32 v118, 16, v104
	v_and_b32_e32 v119, 0xffff0000, v104
	v_lshlrev_b32_e32 v104, 16, v105
	v_and_b32_e32 v105, 0xffff0000, v105
	s_waitcnt lgkmcnt(0)
	v_add_f32_e32 v87, v87, v102
	ds_bpermute_b32 v102, v2, v87
	v_lshlrev_b32_e32 v120, 16, v106
	v_and_b32_e32 v121, 0xffff0000, v106
	v_lshlrev_b32_e32 v106, 16, v107
	v_and_b32_e32 v107, 0xffff0000, v107
	s_waitcnt lgkmcnt(0)
	v_add_f32_e32 v87, v87, v102
	ds_bpermute_b32 v102, v3, v87
	s_waitcnt lgkmcnt(0)
	v_add_f32_e32 v87, v87, v102
	ds_bpermute_b32 v102, v4, v87
	s_waitcnt lgkmcnt(0)
	v_add_f32_e32 v87, v87, v102
	v_fmamk_f32 v87, v87, 0x3c000000, v6
	v_rsq_f32_e32 v102, v87
	s_nop 0
	v_pk_mul_f32 v[96:97], v[96:97], v[102:103] op_sel_hi:[1,0]
	v_pk_mul_f32 v[110:111], v[110:111], v[102:103] op_sel_hi:[1,0]
	v_pk_mul_f32 v[98:99], v[98:99], v[102:103] op_sel_hi:[1,0]
	v_pk_mul_f32 v[100:101], v[100:101], v[102:103] op_sel_hi:[1,0]
	v_pk_mul_f32 v[92:93], v[92:93], v[110:111]
	v_pk_mul_f32 v[94:95], v[94:95], v[96:97]
	v_pk_mul_f32 v[88:89], v[88:89], v[100:101]
	v_pk_mul_f32 v[90:91], v[90:91], v[98:99]
	v_pk_mul_f32 v[94:95], v[94:95], v[104:105]
	v_pk_mul_f32 v[92:93], v[92:93], v[118:119]
	v_pk_mul_f32 v[96:97], v[90:91], v[106:107]
	v_pk_mul_f32 v[90:91], v[88:89], v[120:121]
	v_cvt_pk_bf16_f32 v88, v92, v93
	v_cvt_pk_bf16_f32 v89, v94, v95
	v_cvt_pk_bf16_f32 v90, v90, v91
	v_cvt_pk_bf16_f32 v91, v96, v97
	global_store_dwordx4 v[108:109], v[88:91], off
	s_nop 1
	v_ashrrev_i32_e32 v88, 7, v0
	v_ashrrev_i32_e32 v89, 31, v88
	v_and_b32_e32 v87, 0x3f8, v5
	v_lshlrev_b64 v[96:97], 11, v[88:89]
	v_and_b32_e32 v90, 0x78, v5
	v_lshl_or_b32 v96, v87, 1, v96
	v_lshlrev_b32_e32 v92, 2, v90
	v_lshl_add_u64 v[108:109], s[72:73], 0, v[96:97]
	v_lshl_add_u64 v[100:101], s[4:5], 0, v[96:97]
	v_lshl_add_u64 v[104:105], s[88:89], 0, v[96:97]
	global_load_dwordx4 v[88:91], v92, s[54:55] offset:16
	s_nop 0
	global_load_dwordx4 v[92:95], v92, s[54:55]
	s_nop 0
	global_load_dwordx4 v[96:99], v[108:109], off nt
	s_nop 0
	global_load_dwordx4 v[100:103], v[100:101], off nt
	s_nop 0
	global_load_dwordx4 v[104:107], v[104:105], off nt
	v_add_u32_e32 v0, s8, v0
	v_add_u32_e32 v5, s9, v5
	s_waitcnt vmcnt(6)
	v_lshlrev_b32_e32 v30, 16, v16
	v_and_b32_e32 v31, 0xffff0000, v16
	v_lshlrev_b32_e32 v16, 16, v17
	v_and_b32_e32 v17, 0xffff0000, v17
	v_lshlrev_b32_e32 v34, 16, v20
	v_and_b32_e32 v35, 0xffff0000, v20
	v_lshlrev_b32_e32 v20, 16, v21
	v_and_b32_e32 v21, 0xffff0000, v21
	v_lshlrev_b32_e32 v32, 16, v18
	v_and_b32_e32 v33, 0xffff0000, v18
	v_lshlrev_b32_e32 v18, 16, v19
	v_and_b32_e32 v19, 0xffff0000, v19
	v_lshlrev_b32_e32 v36, 16, v22
	v_and_b32_e32 v37, 0xffff0000, v22
	v_lshlrev_b32_e32 v22, 16, v23
	v_and_b32_e32 v23, 0xffff0000, v23
	v_pk_add_f32 v[30:31], v[30:31], v[34:35]
	v_pk_add_f32 v[16:17], v[16:17], v[20:21]
	v_pk_add_f32 v[20:21], v[32:33], v[36:37]
	v_pk_add_f32 v[18:19], v[18:19], v[22:23]
	v_pk_mul_f32 v[22:23], v[16:17], v[16:17]
	v_pk_mul_f32 v[32:33], v[30:31], v[30:31]
	v_pk_mul_f32 v[34:35], v[18:19], v[18:19]
	v_pk_mul_f32 v[36:37], v[20:21], v[20:21]
	v_pk_mov_b32 v[42:43], v[32:33], v[22:23] op_sel:[1,0]
	v_mov_b32_e32 v33, v23
	v_mov_b32_e32 v22, v34
	v_mov_b32_e32 v23, v36
	v_mov_b32_e32 v36, v35
	v_pk_add_f32 v[32:33], v[42:43], v[32:33]
	v_pk_add_f32 v[22:23], v[22:23], v[36:37]
	v_add_f32_e32 v7, v32, v33
	v_add_f32_e32 v7, v23, v7
	v_add_f32_e32 v7, v22, v7
	ds_bpermute_b32 v22, v1, v7
	v_lshlrev_b32_e32 v38, 16, v24
	v_and_b32_e32 v39, 0xffff0000, v24
	v_lshlrev_b32_e32 v24, 16, v25
	v_and_b32_e32 v25, 0xffff0000, v25
	s_waitcnt lgkmcnt(0)
	v_add_f32_e32 v7, v7, v22
	ds_bpermute_b32 v22, v2, v7
	v_lshlrev_b32_e32 v40, 16, v26
	v_and_b32_e32 v41, 0xffff0000, v26
	v_lshlrev_b32_e32 v26, 16, v27
	v_and_b32_e32 v27, 0xffff0000, v27
	s_waitcnt lgkmcnt(0)
	v_add_f32_e32 v7, v7, v22
	ds_bpermute_b32 v22, v3, v7
	s_waitcnt lgkmcnt(0)
	v_add_f32_e32 v7, v7, v22
	ds_bpermute_b32 v22, v4, v7
	s_waitcnt lgkmcnt(0)
	v_add_f32_e32 v7, v7, v22
	v_fmamk_f32 v7, v7, 0x3c000000, v6
	v_rsq_f32_e32 v22, v7
	s_nop 0
	v_pk_mul_f32 v[16:17], v[16:17], v[22:23] op_sel_hi:[1,0]
	v_pk_mul_f32 v[30:31], v[30:31], v[22:23] op_sel_hi:[1,0]
	v_pk_mul_f32 v[18:19], v[18:19], v[22:23] op_sel_hi:[1,0]
	v_pk_mul_f32 v[20:21], v[20:21], v[22:23] op_sel_hi:[1,0]
	v_pk_mul_f32 v[12:13], v[12:13], v[30:31]
	v_pk_mul_f32 v[14:15], v[14:15], v[16:17]
	v_pk_mul_f32 v[8:9], v[8:9], v[20:21]
	v_pk_mul_f32 v[10:11], v[10:11], v[18:19]
	v_pk_mul_f32 v[14:15], v[14:15], v[24:25]
	v_pk_mul_f32 v[12:13], v[12:13], v[38:39]
	v_pk_mul_f32 v[16:17], v[10:11], v[26:27]
	v_pk_mul_f32 v[10:11], v[8:9], v[40:41]
	v_cvt_pk_bf16_f32 v8, v12, v13
	v_cvt_pk_bf16_f32 v9, v14, v15
	v_cvt_pk_bf16_f32 v10, v10, v11
	v_cvt_pk_bf16_f32 v11, v16, v17
	global_store_dwordx4 v[28:29], v[8:11], off
	s_nop 1
	s_waitcnt vmcnt(1)
	v_lshlrev_b32_e32 v110, 16, v96
	v_and_b32_e32 v111, 0xffff0000, v96
	v_lshlrev_b32_e32 v96, 16, v97
	v_and_b32_e32 v97, 0xffff0000, v97
	v_lshlrev_b32_e32 v114, 16, v100
	v_and_b32_e32 v115, 0xffff0000, v100
	v_lshlrev_b32_e32 v100, 16, v101
	v_and_b32_e32 v101, 0xffff0000, v101
	v_lshlrev_b32_e32 v112, 16, v98
	v_and_b32_e32 v113, 0xffff0000, v98
	v_lshlrev_b32_e32 v98, 16, v99
	v_and_b32_e32 v99, 0xffff0000, v99
	v_lshlrev_b32_e32 v116, 16, v102
	v_and_b32_e32 v117, 0xffff0000, v102
	v_lshlrev_b32_e32 v102, 16, v103
	v_and_b32_e32 v103, 0xffff0000, v103
	v_pk_add_f32 v[110:111], v[110:111], v[114:115]
	v_pk_add_f32 v[96:97], v[96:97], v[100:101]
	v_pk_add_f32 v[100:101], v[112:113], v[116:117]
	v_pk_add_f32 v[98:99], v[98:99], v[102:103]
	v_pk_mul_f32 v[102:103], v[96:97], v[96:97]
	v_pk_mul_f32 v[112:113], v[110:111], v[110:111]
	v_pk_mul_f32 v[114:115], v[98:99], v[98:99]
	v_pk_mul_f32 v[116:117], v[100:101], v[100:101]
	v_pk_mov_b32 v[122:123], v[112:113], v[102:103] op_sel:[1,0]
	v_mov_b32_e32 v113, v103
	v_mov_b32_e32 v102, v114
	v_mov_b32_e32 v103, v116
	v_mov_b32_e32 v116, v115
	v_pk_add_f32 v[112:113], v[122:123], v[112:113]
	v_pk_add_f32 v[102:103], v[102:103], v[116:117]
	v_add_f32_e32 v87, v112, v113
	v_add_f32_e32 v87, v103, v87
	v_add_f32_e32 v87, v102, v87
	ds_bpermute_b32 v102, v1, v87
	v_lshlrev_b32_e32 v118, 16, v104
	v_and_b32_e32 v119, 0xffff0000, v104
	v_lshlrev_b32_e32 v104, 16, v105
	v_and_b32_e32 v105, 0xffff0000, v105
	s_waitcnt lgkmcnt(0)
	v_add_f32_e32 v87, v87, v102
	ds_bpermute_b32 v102, v2, v87
	v_lshlrev_b32_e32 v120, 16, v106
	v_and_b32_e32 v121, 0xffff0000, v106
	v_lshlrev_b32_e32 v106, 16, v107
	v_and_b32_e32 v107, 0xffff0000, v107
	s_waitcnt lgkmcnt(0)
	v_add_f32_e32 v87, v87, v102
	ds_bpermute_b32 v102, v3, v87
	s_waitcnt lgkmcnt(0)
	v_add_f32_e32 v87, v87, v102
	ds_bpermute_b32 v102, v4, v87
	s_waitcnt lgkmcnt(0)
	v_add_f32_e32 v87, v87, v102
	v_fmamk_f32 v87, v87, 0x3c000000, v6
	v_rsq_f32_e32 v102, v87
	s_nop 0
	v_pk_mul_f32 v[96:97], v[96:97], v[102:103] op_sel_hi:[1,0]
	v_pk_mul_f32 v[110:111], v[110:111], v[102:103] op_sel_hi:[1,0]
	v_pk_mul_f32 v[98:99], v[98:99], v[102:103] op_sel_hi:[1,0]
	v_pk_mul_f32 v[100:101], v[100:101], v[102:103] op_sel_hi:[1,0]
	v_pk_mul_f32 v[92:93], v[92:93], v[110:111]
	v_pk_mul_f32 v[94:95], v[94:95], v[96:97]
	v_pk_mul_f32 v[88:89], v[88:89], v[100:101]
	v_pk_mul_f32 v[90:91], v[90:91], v[98:99]
	v_pk_mul_f32 v[94:95], v[94:95], v[104:105]
	v_pk_mul_f32 v[92:93], v[92:93], v[118:119]
	v_pk_mul_f32 v[96:97], v[90:91], v[106:107]
	v_pk_mul_f32 v[90:91], v[88:89], v[120:121]
	v_cvt_pk_bf16_f32 v88, v92, v93
	v_cvt_pk_bf16_f32 v89, v94, v95
	v_cvt_pk_bf16_f32 v90, v90, v91
	v_cvt_pk_bf16_f32 v91, v96, v97
	global_store_dwordx4 v[108:109], v[88:91], off
	s_nop 1
	s_branch .LBB0_587
